# norm phase: device-scope write-through (sc1) on the 32 H / XS stores so the L2 writeback at the following grid barrier has less to flush
# speedup vs baseline: 1.0068x; 1.0004x over previous
.LBB0_88:
	s_waitcnt vmcnt(21)
	v_pk_mul_f32 v[112:113], v[92:93], v[92:93]
	v_pk_mul_f32 v[114:115], v[132:133], v[132:133]
	s_waitcnt vmcnt(15)
	v_pk_mul_f32 v[108:109], v[94:95], v[94:95]
	v_pk_mul_f32 v[110:111], v[134:135], v[134:135]
	s_waitcnt vmcnt(8)
	v_mov_b32_e32 v116, v112
	v_mov_b32_e32 v117, v114
	v_mov_b32_e32 v114, v113
	v_pk_mul_f32 v[104:105], v[138:139], v[138:139]
	v_pk_mul_f32 v[106:107], v[136:137], v[136:137]
	v_pk_add_f32 v[112:113], v[116:117], v[114:115]
	v_mov_b32_e32 v114, v108
	v_mov_b32_e32 v115, v110
	v_mov_b32_e32 v110, v109
	v_pk_add_f32 v[108:109], v[114:115], v[110:111]
	v_pk_mov_b32 v[110:111], v[106:107], v[104:105] op_sel:[1,0]
	v_mov_b32_e32 v107, v105
	v_pk_add_f32 v[104:105], v[110:111], v[106:107]
	v_pk_add_f32 v[108:109], v[112:113], v[108:109]
	v_pk_add_f32 v[104:105], v[104:105], v[104:105] op_sel_hi:[0,1]
	v_mul_f32_e32 v104, v140, v140
	v_pk_fma_f32 v[106:107], v[140:141], v[140:141], v[104:105] op_sel_hi:[1,1,0]
	v_mul_f32_e32 v104, v142, v142
	v_pk_add_f32 v[108:109], v[108:109], v[108:109] op_sel_hi:[0,1]
	v_pk_fma_f32 v[110:111], v[142:143], v[142:143], v[104:105] op_sel_hi:[1,1,0]
	v_pk_add_f32 v[76:77], v[76:77], 1.0 op_sel_hi:[1,0]
	v_pk_add_f32 v[72:73], v[72:73], 1.0 op_sel_hi:[1,0]
	s_waitcnt vmcnt(7)
	v_pk_add_f32 v[68:69], v[68:69], 1.0 op_sel_hi:[1,0]
	v_mul_f32_e32 v106, v144, v144
	v_mul_f32_e32 v110, v145, v145
	v_mul_f32_e32 v104, v146, v146
	v_mul_f32_e32 v108, v147, v147
	v_pk_mul_f32 v[100:101], v[12:13], v[76:77]
	v_pk_mul_f32 v[76:77], v[16:17], v[72:73]
	v_pk_mul_f32 v[72:73], v[20:21], v[68:69]
	s_waitcnt vmcnt(3)
	v_pk_add_f32 v[68:69], v[86:87], 1.0 op_sel_hi:[1,0]
	v_pk_mul_f32 v[86:87], v[150:151], v[150:151]
	v_pk_mul_f32 v[102:103], v[148:149], v[148:149]
	v_pk_add_f32 v[106:107], v[106:107], v[110:111]
	v_pk_add_f32 v[104:105], v[104:105], v[108:109]
	v_pk_add_f32 v[98:99], v[98:99], 1.0 op_sel_hi:[1,0]
	v_pk_add_f32 v[104:105], v[106:107], v[104:105]
	v_pk_mov_b32 v[106:107], v[102:103], v[86:87] op_sel:[1,0]
	v_mov_b32_e32 v103, v87
	v_pk_add_f32 v[86:87], v[106:107], v[102:103]
	v_pk_add_f32 v[104:105], v[104:105], v[104:105] op_sel_hi:[0,1]
	v_pk_add_f32 v[86:87], v[86:87], v[86:87] op_sel_hi:[0,1]
	v_mul_f32_e32 v86, v152, v152
	v_pk_fma_f32 v[102:103], v[152:153], v[152:153], v[86:87] op_sel_hi:[1,1,0]
	v_mul_f32_e32 v86, v154, v154
	v_pk_fma_f32 v[106:107], v[154:155], v[154:155], v[86:87] op_sel_hi:[1,1,0]
	v_mul_f32_e32 v102, v160, v160
	v_mul_f32_e32 v106, v161, v161
	v_mul_f32_e32 v86, v162, v162
	v_mul_f32_e32 v104, v163, v163
	v_pk_add_f32 v[102:103], v[102:103], v[106:107]
	v_pk_add_f32 v[86:87], v[86:87], v[104:105]
	v_pk_add_f32 v[96:97], v[96:97], 1.0 op_sel_hi:[1,0]
	v_pk_add_f32 v[86:87], v[102:103], v[86:87]
	v_pk_mul_f32 v[98:99], v[2:3], v[98:99]
	v_add_f32_e32 v86, v86, v87
	v_pk_mul_f32 v[96:97], v[0:1], v[96:97]
	v_pk_add_f32 v[88:89], v[88:89], 1.0 op_sel_hi:[1,0]
	v_add_f32_dpp v86, v86, v86 row_ror:8 row_mask:0xf bank_mask:0xf bound_ctrl:1
	v_pk_add_f32 v[90:91], v[90:91], 1.0 op_sel_hi:[1,0]
	v_pk_mul_f32 v[88:89], v[4:5], v[88:89]
	v_add_f32_dpp v86, v86, v86 row_ror:4 row_mask:0xf bank_mask:0xf bound_ctrl:1
	v_pk_mul_f32 v[90:91], v[6:7], v[90:91]
	v_pk_add_f32 v[80:81], v[80:81], 1.0 op_sel_hi:[1,0]
	v_add_f32_dpp v86, v86, v86 row_ror:2 row_mask:0xf bank_mask:0xf bound_ctrl:1
	v_pk_add_f32 v[82:83], v[82:83], 1.0 op_sel_hi:[1,0]
	v_pk_mul_f32 v[80:81], v[8:9], v[80:81]
	v_add_f32_dpp v86, v86, v86 row_ror:1 row_mask:0xf bank_mask:0xf bound_ctrl:1
	v_pk_mul_f32 v[82:83], v[10:11], v[82:83]
	v_readlane_b32 s1, v86, 16
	v_readlane_b32 s2, v86, 48
	v_readlane_b32 s12, v86, 0
	v_readlane_b32 s13, v86, 32
	v_mov_b32_e32 v86, s1
	v_mov_b32_e32 v87, s2
	v_pk_add_f32 v[86:87], s[12:13], v[86:87]
	v_pk_add_f32 v[78:79], v[78:79], 1.0 op_sel_hi:[1,0]
	v_add_f32_e32 v86, v86, v87
	v_fmamk_f32 v86, v86, 0x3a000000, v173
	v_mul_f32_e32 v87, 0x4f800000, v86
	v_cmp_gt_f32_e32 vcc, s19, v86
	v_pk_mul_f32 v[78:79], v[14:15], v[78:79]
	v_pk_add_f32 v[74:75], v[74:75], 1.0 op_sel_hi:[1,0]
	v_cndmask_b32_e32 v86, v86, v87, vcc
	v_sqrt_f32_e32 v87, v86
	v_pk_mul_f32 v[74:75], v[18:19], v[74:75]
	v_pk_add_f32 v[70:71], v[70:71], 1.0 op_sel_hi:[1,0]
	v_pk_add_f32 v[84:85], v[84:85], 1.0 op_sel_hi:[1,0]
	v_add_u32_e32 v102, -1, v87
	v_fma_f32 v103, -v102, v87, v86
	v_cmp_ge_f32_e64 s[38:39], 0, v103
	v_add_u32_e32 v103, 1, v87
	v_pk_mul_f32 v[70:71], v[22:23], v[70:71]
	v_cndmask_b32_e64 v102, v87, v102, s[38:39]
	v_fma_f32 v87, -v103, v87, v86
	v_cmp_lt_f32_e64 s[38:39], 0, v87
	v_pk_mul_f32 v[84:85], v[24:25], v[84:85]
	v_pk_mul_f32 v[68:69], v[26:27], v[68:69]
	v_cndmask_b32_e64 v87, v102, v103, s[38:39]
	v_mul_f32_e32 v102, 0x37800000, v87
	v_cndmask_b32_e32 v87, v87, v102, vcc
	v_cmp_class_f32_e32 vcc, v86, v244
	s_waitcnt vmcnt(1)
	v_pk_add_f32 v[64:65], v[64:65], 1.0 op_sel_hi:[1,0]
	v_pk_add_f32 v[66:67], v[66:67], 1.0 op_sel_hi:[1,0]
	v_cndmask_b32_e32 v102, v87, v86, vcc
	v_div_scale_f32 v103, s[12:13], v102, v102, 1.0
	v_rcp_f32_e32 v104, v103
	v_lshlrev_b64 v[86:87], 12, v[236:237]
	v_pk_mul_f32 v[64:65], v[28:29], v[64:65]
	v_pk_mul_f32 v[66:67], v[30:31], v[66:67]
	v_fma_f32 v105, -v103, v104, 1.0
	v_fmac_f32_e32 v104, v105, v104
	v_div_scale_f32 v105, vcc, 1.0, v102, 1.0
	v_mul_f32_e32 v106, v105, v104
	v_fma_f32 v107, -v103, v106, v105
	v_fmac_f32_e32 v106, v107, v104
	v_fma_f32 v103, -v103, v106, v105
	v_div_fmas_f32 v103, v103, v104, v106
	v_div_fixup_f32 v102, v103, v102, 1.0
	v_pk_mul_f32 v[92:93], v[92:93], v[102:103] op_sel_hi:[1,0]
	v_pk_mul_f32 v[94:95], v[94:95], v[102:103] op_sel_hi:[1,0]
	v_pk_fma_f32 v[60:61], v[96:97], v[92:93], v[60:61]
	v_pk_fma_f32 v[62:63], v[98:99], v[94:95], v[62:63]
	v_cvt_pk_bf16_f32 v60, v60, v61
	v_add_u32_e32 v234, s82, v234
	v_cvt_pk_bf16_f32 v61, v62, v63
	v_lshl_add_u64 v[62:63], v[188:189], 0, v[86:87]
	global_store_dwordx2 v[62:63], v[60:61], off sc1
	v_pk_mul_f32 v[60:61], v[132:133], v[102:103] op_sel_hi:[1,0]
	v_pk_mul_f32 v[86:87], v[134:135], v[102:103] op_sel_hi:[1,0]
	v_pk_fma_f32 v[56:57], v[88:89], v[60:61], v[56:57]
	v_pk_fma_f32 v[58:59], v[90:91], v[86:87], v[58:59]
	v_cvt_pk_bf16_f32 v56, v56, v57
	s_movk_i32 s1, 0x23ff
	v_cvt_pk_bf16_f32 v57, v58, v59
	global_store_dwordx2 v[62:63], v[56:57], off offset:512 sc1
	v_pk_mul_f32 v[56:57], v[136:137], v[102:103] op_sel_hi:[1,0]
	v_pk_mul_f32 v[58:59], v[138:139], v[102:103] op_sel_hi:[1,0]
	v_pk_fma_f32 v[52:53], v[80:81], v[56:57], v[52:53]
	v_pk_fma_f32 v[54:55], v[82:83], v[58:59], v[54:55]
	v_cvt_pk_bf16_f32 v52, v52, v53
	v_readlane_b32 s12, v254, 45
	v_cvt_pk_bf16_f32 v53, v54, v55
	global_store_dwordx2 v[62:63], v[52:53], off offset:1024 sc1
	v_pk_mul_f32 v[52:53], v[140:141], v[102:103] op_sel_hi:[1,0]
	v_pk_mul_f32 v[54:55], v[142:143], v[102:103] op_sel_hi:[1,0]
	v_pk_fma_f32 v[48:49], v[100:101], v[52:53], v[48:49]
	v_pk_fma_f32 v[50:51], v[78:79], v[54:55], v[50:51]
	v_cvt_pk_bf16_f32 v48, v48, v49
	v_readlane_b32 s13, v254, 46
	v_cvt_pk_bf16_f32 v49, v50, v51
	global_store_dwordx2 v[62:63], v[48:49], off offset:1536 sc1
	v_pk_mul_f32 v[48:49], v[144:145], v[102:103] op_sel_hi:[1,0]
	v_pk_mul_f32 v[50:51], v[146:147], v[102:103] op_sel_hi:[1,0]
	v_pk_fma_f32 v[44:45], v[76:77], v[48:49], v[44:45]
	v_pk_fma_f32 v[46:47], v[74:75], v[50:51], v[46:47]
	v_cvt_pk_bf16_f32 v44, v44, v45
	v_lshl_add_u64 v[186:187], v[186:187], 0, s[82:83]
	v_cvt_pk_bf16_f32 v45, v46, v47
	global_store_dwordx2 v[62:63], v[44:45], off offset:2048 sc1
	v_pk_mul_f32 v[44:45], v[148:149], v[102:103] op_sel_hi:[1,0]
	v_pk_mul_f32 v[46:47], v[150:151], v[102:103] op_sel_hi:[1,0]
	v_pk_fma_f32 v[36:37], v[72:73], v[44:45], v[36:37]
	v_pk_fma_f32 v[38:39], v[70:71], v[46:47], v[38:39]
	v_cvt_pk_bf16_f32 v36, v36, v37
	v_lshl_add_u64 v[232:233], v[232:233], 0, s[12:13]
	v_cvt_pk_bf16_f32 v37, v38, v39
	global_store_dwordx2 v[62:63], v[36:37], off offset:2560 sc1
	v_pk_mul_f32 v[36:37], v[152:153], v[102:103] op_sel_hi:[1,0]
	v_pk_mul_f32 v[38:39], v[154:155], v[102:103] op_sel_hi:[1,0]
	v_pk_fma_f32 v[36:37], v[84:85], v[36:37], v[40:41]
	v_pk_fma_f32 v[38:39], v[68:69], v[38:39], v[42:43]
	v_cvt_pk_bf16_f32 v36, v36, v37
	s_nop 0
	v_cvt_pk_bf16_f32 v37, v38, v39
	global_store_dwordx2 v[62:63], v[36:37], off offset:3072 sc1
	v_pk_mul_f32 v[36:37], v[156:157], v[102:103] op_sel_hi:[1,0]
	v_pk_mul_f32 v[38:39], v[158:159], v[102:103] op_sel_hi:[1,0]
	s_waitcnt vmcnt(7)
	v_pk_fma_f32 v[32:33], v[64:65], v[36:37], v[32:33]
	v_pk_fma_f32 v[34:35], v[66:67], v[38:39], v[34:35]
	v_cvt_pk_bf16_f32 v32, v32, v33
	s_nop 0
	v_cvt_pk_bf16_f32 v33, v34, v35
	global_store_dwordx2 v[62:63], v[32:33], off offset:3584 sc1
	v_add_u32_e32 v32, 0x2000, v234
	v_cmp_lt_i32_e32 vcc, s1, v32
	s_or_b64 s[26:27], vcc, s[26:27]
	s_andn2_b64 exec, exec, s[26:27]
	s_cbranch_execz .LBB0_96

.LBB0_92:
	v_ashrrev_i32_e32 v33, 31, v32
	v_lshlrev_b64 v[32:33], 13, v[32:33]
	v_lshl_add_u64 v[32:33], s[12:13], 0, v[32:33]
	v_lshl_add_u64 v[34:35], v[32:33], 0, v[174:175]
	global_load_dwordx4 v[96:99], v[192:193], off
	global_load_dwordx4 v[60:63], v[190:191], off
	global_load_dwordx4 v[112:115], v[34:35], off
	global_load_dwordx4 v[104:107], v[34:35], off offset:1024
	global_load_dwordx4 v[88:91], v[196:197], off
	global_load_dwordx4 v[56:59], v[194:195], off
	global_load_dwordx4 v[80:83], v[200:201], off
	global_load_dwordx4 v[52:55], v[198:199], off
	global_load_dwordx4 v[108:111], v[34:35], off offset:2048
	global_load_dwordx4 v[100:103], v[34:35], off offset:3072
	global_load_dwordx4 v[76:79], v[204:205], off
	global_load_dwordx4 v[48:51], v[202:203], off
	v_mov_b32_e32 v165, v175
	v_mov_b32_e32 v167, v175
	v_lshl_add_u64 v[34:35], v[32:33], 0, v[164:165]
	v_lshl_add_u64 v[36:37], v[32:33], 0, v[166:167]
	v_mov_b32_e32 v169, v175
	v_mov_b32_e32 v171, v175
	global_load_dwordx4 v[72:75], v[208:209], off
	global_load_dwordx4 v[44:47], v[206:207], off
	global_load_dwordx4 v[120:123], v[34:35], off
	global_load_dwordx4 v[116:119], v[36:37], off
	global_load_dwordx4 v[68:71], v[212:213], off
	s_nop 0
	global_load_dwordx4 v[36:39], v[210:211], off
	v_lshl_add_u64 v[34:35], v[32:33], 0, v[168:169]
	v_lshl_add_u64 v[32:33], v[32:33], 0, v[170:171]
	global_load_dwordx4 v[128:131], v[34:35], off
	global_load_dwordx4 v[124:127], v[32:33], off
	global_load_dwordx4 v[84:87], v[216:217], off
	global_load_dwordx4 v[40:43], v[214:215], off
	global_load_dwordx4 v[64:67], v[220:221], off
	s_nop 0
	global_load_dwordx4 v[32:35], v[218:219], off
	s_and_b64 vcc, exec, s[24:25]
	s_cbranch_vccz .LBB0_94
	v_ashrrev_i32_e32 v235, 31, v234
	v_lshlrev_b64 v[92:93], 13, v[234:235]
	v_lshl_add_u64 v[156:157], s[8:9], 0, v[92:93]
	v_lshl_add_u64 v[144:145], v[156:157], 0, v[174:175]
	global_load_dwordx4 v[92:95], v[144:145], off
	v_add_co_u32_e32 v142, vcc, 0x800000, v144
	s_mov_b32 s1, 0x801000
	s_nop 0
	v_addc_co_u32_e32 v143, vcc, 0, v145, vcc
	v_add_co_u32_e32 v148, vcc, 0x1000000, v144
	s_nop 1
	v_addc_co_u32_e32 v149, vcc, 0, v145, vcc
	v_add_co_u32_e32 v152, vcc, 0x1800000, v144
	global_load_dwordx4 v[248:251], v[142:143], off
	s_waitcnt vmcnt(1)
	v_pk_add_f32 v[132:133], v[94:95], 0 op_sel_hi:[1,0]
	v_pk_add_f32 v[134:135], v[92:93], 0 op_sel_hi:[1,0]
	v_addc_co_u32_e32 v153, vcc, 0, v145, vcc
	v_add_co_u32_e32 v154, vcc, 0x2000000, v144
	global_load_dwordx4 v[92:95], v[148:149], off
	s_waitcnt vmcnt(1)
	v_pk_add_f32 v[132:133], v[132:133], v[250:251]
	v_pk_add_f32 v[134:135], v[134:135], v[248:249]
	v_addc_co_u32_e32 v155, vcc, 0, v145, vcc
	v_add_co_u32_e32 v150, vcc, 0x2800000, v144
	global_load_dwordx4 v[248:251], v[152:153], off
	s_waitcnt vmcnt(1)
	v_pk_add_f32 v[132:133], v[132:133], v[94:95]
	v_pk_add_f32 v[134:135], v[134:135], v[92:93]
	v_addc_co_u32_e32 v151, vcc, 0, v145, vcc
	v_add_co_u32_e32 v146, vcc, 0x3000000, v144
	global_load_dwordx4 v[92:95], v[154:155], off
	s_waitcnt vmcnt(1)
	v_pk_add_f32 v[132:133], v[132:133], v[250:251]
	v_pk_add_f32 v[134:135], v[134:135], v[248:249]
	v_addc_co_u32_e32 v147, vcc, 0, v145, vcc
	v_add_co_u32_e32 v140, vcc, 0x3800000, v144
	global_load_dwordx4 v[248:251], v[150:151], off
	s_waitcnt vmcnt(1)
	v_pk_add_f32 v[132:133], v[132:133], v[94:95]
	v_pk_add_f32 v[134:135], v[134:135], v[92:93]
	v_addc_co_u32_e32 v141, vcc, 0, v145, vcc
	global_load_dwordx4 v[92:95], v[146:147], off
	s_waitcnt vmcnt(1)
	v_pk_add_f32 v[132:133], v[132:133], v[250:251]
	v_pk_add_f32 v[134:135], v[134:135], v[248:249]
	global_load_dwordx4 v[248:251], v[140:141], off
	s_waitcnt vmcnt(1)
	v_pk_add_f32 v[132:133], v[132:133], v[94:95]
	v_pk_add_f32 v[134:135], v[134:135], v[92:93]
	global_load_dwordx4 v[92:95], v[222:223], off
	s_waitcnt vmcnt(1)
	v_pk_add_f32 v[132:133], v[132:133], v[250:251]
	v_pk_add_f32 v[134:135], v[134:135], v[248:249]
	global_load_dwordx4 v[248:251], v[144:145], off offset:1024
	s_waitcnt vmcnt(1)
	v_pk_fma_f32 v[94:95], v[132:133], v[94:95], v[114:115]
	v_pk_fma_f32 v[92:93], v[134:135], v[92:93], v[112:113]
	global_load_dwordx4 v[132:135], v[142:143], off offset:1024
	s_waitcnt vmcnt(1)
	v_pk_add_f32 v[136:137], v[250:251], 0 op_sel_hi:[1,0]
	v_pk_add_f32 v[138:139], v[248:249], 0 op_sel_hi:[1,0]
	global_load_dwordx4 v[248:251], v[148:149], off offset:1024
	s_waitcnt vmcnt(1)
	v_pk_add_f32 v[136:137], v[136:137], v[134:135]
	v_pk_add_f32 v[138:139], v[138:139], v[132:133]
	global_load_dwordx4 v[132:135], v[152:153], off offset:1024
	s_waitcnt vmcnt(1)
	v_pk_add_f32 v[136:137], v[136:137], v[250:251]
	v_pk_add_f32 v[138:139], v[138:139], v[248:249]
	global_load_dwordx4 v[248:251], v[154:155], off offset:1024
	s_waitcnt vmcnt(1)
	v_pk_add_f32 v[136:137], v[136:137], v[134:135]
	v_pk_add_f32 v[138:139], v[138:139], v[132:133]
	global_load_dwordx4 v[132:135], v[150:151], off offset:1024
	s_waitcnt vmcnt(1)
	v_pk_add_f32 v[136:137], v[136:137], v[250:251]
	v_pk_add_f32 v[138:139], v[138:139], v[248:249]
	global_load_dwordx4 v[248:251], v[146:147], off offset:1024
	s_waitcnt vmcnt(1)
	v_pk_add_f32 v[136:137], v[136:137], v[134:135]
	v_pk_add_f32 v[138:139], v[138:139], v[132:133]
	global_load_dwordx4 v[132:135], v[140:141], off offset:1024
	s_waitcnt vmcnt(1)
	v_pk_add_f32 v[136:137], v[136:137], v[250:251]
	v_pk_add_f32 v[138:139], v[138:139], v[248:249]
	global_load_dwordx4 v[248:251], v[224:225], off
	s_waitcnt vmcnt(1)
	v_pk_add_f32 v[136:137], v[136:137], v[134:135]
	v_pk_add_f32 v[138:139], v[138:139], v[132:133]
	s_waitcnt vmcnt(0)
	v_pk_fma_f32 v[134:135], v[136:137], v[250:251], v[106:107]
	v_pk_fma_f32 v[132:133], v[138:139], v[248:249], v[104:105]
	global_load_dwordx4 v[136:139], v[144:145], off offset:2048
	global_load_dwordx4 v[248:251], v[142:143], off offset:2048
	s_waitcnt vmcnt(1)
	v_pk_add_f32 v[158:159], v[138:139], 0 op_sel_hi:[1,0]
	v_pk_add_f32 v[160:161], v[136:137], 0 op_sel_hi:[1,0]
	global_load_dwordx4 v[136:139], v[148:149], off offset:2048
	s_waitcnt vmcnt(1)
	v_pk_add_f32 v[158:159], v[158:159], v[250:251]
	v_pk_add_f32 v[160:161], v[160:161], v[248:249]
	global_load_dwordx4 v[248:251], v[152:153], off offset:2048
	s_waitcnt vmcnt(1)
	v_pk_add_f32 v[158:159], v[158:159], v[138:139]
	v_pk_add_f32 v[160:161], v[160:161], v[136:137]
	global_load_dwordx4 v[136:139], v[154:155], off offset:2048
	s_waitcnt vmcnt(1)
	v_pk_add_f32 v[158:159], v[158:159], v[250:251]
	v_pk_add_f32 v[160:161], v[160:161], v[248:249]
	global_load_dwordx4 v[248:251], v[150:151], off offset:2048
	s_waitcnt vmcnt(1)
	v_pk_add_f32 v[158:159], v[158:159], v[138:139]
	v_pk_add_f32 v[160:161], v[160:161], v[136:137]
	global_load_dwordx4 v[136:139], v[146:147], off offset:2048
	s_waitcnt vmcnt(1)
	v_pk_add_f32 v[158:159], v[158:159], v[250:251]
	v_pk_add_f32 v[160:161], v[160:161], v[248:249]
	global_load_dwordx4 v[248:251], v[140:141], off offset:2048
	s_waitcnt vmcnt(1)
	v_pk_add_f32 v[158:159], v[158:159], v[138:139]
	v_pk_add_f32 v[160:161], v[160:161], v[136:137]
	global_load_dwordx4 v[136:139], v[226:227], off
	s_waitcnt vmcnt(1)
	v_pk_add_f32 v[158:159], v[158:159], v[250:251]
	v_pk_add_f32 v[160:161], v[160:161], v[248:249]
	global_load_dwordx4 v[248:251], v[144:145], off offset:3072
	s_waitcnt vmcnt(1)
	v_pk_fma_f32 v[138:139], v[158:159], v[138:139], v[110:111]
	v_pk_fma_f32 v[136:137], v[160:161], v[136:137], v[108:109]
	global_load_dwordx4 v[158:161], v[142:143], off offset:3072
	s_waitcnt vmcnt(1)
	v_pk_add_f32 v[162:163], v[250:251], 0 op_sel_hi:[1,0]
	v_pk_add_f32 v[180:181], v[248:249], 0 op_sel_hi:[1,0]
	global_load_dwordx4 v[248:251], v[148:149], off offset:3072
	s_waitcnt vmcnt(1)
	v_pk_add_f32 v[142:143], v[162:163], v[160:161]
	v_pk_add_f32 v[162:163], v[180:181], v[158:159]
	global_load_dwordx4 v[158:161], v[152:153], off offset:3072
	s_waitcnt vmcnt(1)
	v_pk_add_f32 v[142:143], v[142:143], v[250:251]
	v_pk_add_f32 v[148:149], v[162:163], v[248:249]
	global_load_dwordx4 v[152:155], v[154:155], off offset:3072
	s_waitcnt vmcnt(1)
	v_pk_add_f32 v[148:149], v[148:149], v[158:159]
	v_pk_add_f32 v[142:143], v[142:143], v[160:161]
	v_add_co_u32_e32 v158, vcc, s1, v144
	s_mov_b32 s1, 0x1001000
	s_nop 0
	v_addc_co_u32_e32 v159, vcc, 0, v145, vcc
	v_add_co_u32_e32 v160, vcc, s1, v144
	s_mov_b32 s1, 0x1801000
	s_nop 0
	v_addc_co_u32_e32 v161, vcc, 0, v145, vcc
	v_add_co_u32_e32 v162, vcc, s1, v144
	s_mov_b32 s1, 0x2001000
	s_nop 0
	v_addc_co_u32_e32 v163, vcc, 0, v145, vcc
	v_add_co_u32_e32 v236, vcc, s1, v144
	s_mov_b32 s1, 0x2801000
	s_nop 0
	v_addc_co_u32_e32 v237, vcc, 0, v145, vcc
	v_add_co_u32_e32 v238, vcc, s1, v144
	s_mov_b32 s1, 0x3001000
	s_nop 0
	v_addc_co_u32_e32 v239, vcc, 0, v145, vcc
	v_add_co_u32_e32 v240, vcc, s1, v144
	s_mov_b32 s1, 0x3801000
	s_nop 0
	v_addc_co_u32_e32 v241, vcc, 0, v145, vcc
	v_add_co_u32_e32 v242, vcc, s1, v144
	s_movk_i32 s1, 0xf000
	s_nop 0
	v_addc_co_u32_e32 v243, vcc, 0, v145, vcc
	global_load_dwordx4 v[248:251], v[150:151], off offset:3072
	s_waitcnt vmcnt(1)
	v_pk_add_f32 v[152:153], v[148:149], v[152:153]
	v_pk_add_f32 v[142:143], v[142:143], v[154:155]
	global_load_dwordx4 v[146:149], v[146:147], off offset:3072
	s_waitcnt vmcnt(1)
	v_pk_add_f32 v[142:143], v[142:143], v[250:251]
	v_pk_add_f32 v[150:151], v[152:153], v[248:249]
	global_load_dwordx4 v[248:251], v[140:141], off offset:3072
	s_waitcnt vmcnt(1)
	v_pk_add_f32 v[148:149], v[142:143], v[148:149]
	v_pk_add_f32 v[146:147], v[150:151], v[146:147]
	global_load_dwordx4 v[140:143], v[228:229], off
	s_waitcnt vmcnt(1)
	v_pk_add_f32 v[148:149], v[148:149], v[250:251]
	v_pk_add_f32 v[146:147], v[146:147], v[248:249]
	s_waitcnt vmcnt(0)
	v_pk_fma_f32 v[140:141], v[146:147], v[140:141], v[100:101]
	v_lshl_add_u64 v[146:147], v[156:157], 0, v[164:165]
	v_pk_fma_f32 v[142:143], v[148:149], v[142:143], v[102:103]
	global_load_dwordx4 v[146:149], v[146:147], off
	global_load_dwordx4 v[248:251], v[158:159], off
	s_waitcnt vmcnt(1)
	v_pk_add_f32 v[150:151], v[148:149], 0 op_sel_hi:[1,0]
	v_pk_add_f32 v[152:153], v[146:147], 0 op_sel_hi:[1,0]
	global_load_dwordx4 v[146:149], v[160:161], off
	s_waitcnt vmcnt(1)
	v_pk_add_f32 v[150:151], v[150:151], v[250:251]
	v_pk_add_f32 v[152:153], v[152:153], v[248:249]
	global_load_dwordx4 v[248:251], v[162:163], off
	s_waitcnt vmcnt(1)
	v_pk_add_f32 v[150:151], v[150:151], v[148:149]
	v_pk_add_f32 v[152:153], v[152:153], v[146:147]
	global_load_dwordx4 v[146:149], v[236:237], off
	s_waitcnt vmcnt(1)
	v_pk_add_f32 v[150:151], v[150:151], v[250:251]
	v_pk_add_f32 v[152:153], v[152:153], v[248:249]
	global_load_dwordx4 v[248:251], v[238:239], off
	s_waitcnt vmcnt(1)
	v_pk_add_f32 v[150:151], v[150:151], v[148:149]
	v_pk_add_f32 v[152:153], v[152:153], v[146:147]
	global_load_dwordx4 v[146:149], v[240:241], off
	s_waitcnt vmcnt(1)
	v_pk_add_f32 v[150:151], v[150:151], v[250:251]
	v_pk_add_f32 v[152:153], v[152:153], v[248:249]
	global_load_dwordx4 v[248:251], v[242:243], off
	s_waitcnt vmcnt(1)
	v_pk_add_f32 v[148:149], v[150:151], v[148:149]
	v_pk_add_f32 v[150:151], v[152:153], v[146:147]
	global_load_dwordx4 v[144:147], v[230:231], off offset:-4096
	s_waitcnt vmcnt(1)
	v_pk_add_f32 v[148:149], v[148:149], v[250:251]
	v_pk_add_f32 v[150:151], v[150:151], v[248:249]
	s_waitcnt vmcnt(0)
	v_pk_fma_f32 v[146:147], v[148:149], v[146:147], v[122:123]
	v_lshl_add_u64 v[148:149], v[156:157], 0, v[166:167]
	v_pk_fma_f32 v[144:145], v[150:151], v[144:145], v[120:121]
	global_load_dwordx4 v[148:151], v[148:149], off
	global_load_dwordx4 v[248:251], v[158:159], off offset:1024
	s_waitcnt vmcnt(1)
	v_pk_add_f32 v[152:153], v[150:151], 0 op_sel_hi:[1,0]
	v_pk_add_f32 v[154:155], v[148:149], 0 op_sel_hi:[1,0]
	global_load_dwordx4 v[148:151], v[160:161], off offset:1024
	s_waitcnt vmcnt(1)
	v_pk_add_f32 v[152:153], v[152:153], v[250:251]
	v_pk_add_f32 v[154:155], v[154:155], v[248:249]
	global_load_dwordx4 v[248:251], v[162:163], off offset:1024
	s_waitcnt vmcnt(1)
	v_pk_add_f32 v[152:153], v[152:153], v[150:151]
	v_pk_add_f32 v[154:155], v[154:155], v[148:149]
	global_load_dwordx4 v[148:151], v[236:237], off offset:1024
	s_waitcnt vmcnt(1)
	v_pk_add_f32 v[152:153], v[152:153], v[250:251]
	v_pk_add_f32 v[154:155], v[154:155], v[248:249]
	global_load_dwordx4 v[248:251], v[238:239], off offset:1024
	s_waitcnt vmcnt(1)
	v_pk_add_f32 v[152:153], v[152:153], v[150:151]
	v_pk_add_f32 v[154:155], v[154:155], v[148:149]
	global_load_dwordx4 v[148:151], v[240:241], off offset:1024
	s_waitcnt vmcnt(1)
	v_pk_add_f32 v[152:153], v[152:153], v[250:251]
	v_pk_add_f32 v[154:155], v[154:155], v[248:249]
	global_load_dwordx4 v[248:251], v[242:243], off offset:1024
	s_waitcnt vmcnt(1)
	v_pk_add_f32 v[152:153], v[152:153], v[150:151]
	v_pk_add_f32 v[154:155], v[154:155], v[148:149]
	global_load_dwordx4 v[148:151], v[230:231], off offset:-3072
	s_waitcnt vmcnt(1)
	v_pk_add_f32 v[152:153], v[152:153], v[250:251]
	v_pk_add_f32 v[154:155], v[154:155], v[248:249]
	s_waitcnt vmcnt(0)
	v_pk_fma_f32 v[150:151], v[152:153], v[150:151], v[118:119]
	v_lshl_add_u64 v[152:153], v[156:157], 0, v[168:169]
	v_pk_fma_f32 v[148:149], v[154:155], v[148:149], v[116:117]
	global_load_dwordx4 v[152:155], v[152:153], off
	v_lshl_add_u64 v[156:157], v[156:157], 0, v[170:171]
	global_load_dwordx4 v[248:251], v[158:159], off offset:2048
	s_waitcnt vmcnt(1)
	v_pk_add_f32 v[180:181], v[154:155], 0 op_sel_hi:[1,0]
	v_pk_add_f32 v[182:183], v[152:153], 0 op_sel_hi:[1,0]
	global_load_dwordx4 v[152:155], v[160:161], off offset:2048
	s_waitcnt vmcnt(1)
	v_pk_add_f32 v[180:181], v[180:181], v[250:251]
	v_pk_add_f32 v[182:183], v[182:183], v[248:249]
	global_load_dwordx4 v[248:251], v[162:163], off offset:2048
	s_waitcnt vmcnt(1)
	v_pk_add_f32 v[180:181], v[180:181], v[154:155]
	v_pk_add_f32 v[182:183], v[182:183], v[152:153]
	global_load_dwordx4 v[152:155], v[236:237], off offset:2048
	s_waitcnt vmcnt(1)
	v_pk_add_f32 v[180:181], v[180:181], v[250:251]
	v_pk_add_f32 v[182:183], v[182:183], v[248:249]
	global_load_dwordx4 v[248:251], v[238:239], off offset:2048
	s_waitcnt vmcnt(1)
	v_pk_add_f32 v[180:181], v[180:181], v[154:155]
	v_pk_add_f32 v[182:183], v[182:183], v[152:153]
	global_load_dwordx4 v[152:155], v[240:241], off offset:2048
	s_waitcnt vmcnt(1)
	v_pk_add_f32 v[180:181], v[180:181], v[250:251]
	v_pk_add_f32 v[182:183], v[182:183], v[248:249]
	global_load_dwordx4 v[248:251], v[242:243], off offset:2048
	s_waitcnt vmcnt(1)
	v_pk_add_f32 v[180:181], v[180:181], v[154:155]
	v_pk_add_f32 v[182:183], v[182:183], v[152:153]
	global_load_dwordx4 v[152:155], v[230:231], off offset:-2048
	s_waitcnt vmcnt(1)
	v_pk_add_f32 v[180:181], v[180:181], v[250:251]
	v_pk_add_f32 v[182:183], v[182:183], v[248:249]
	global_load_dwordx4 v[248:251], v[156:157], off
	s_waitcnt vmcnt(1)
	v_pk_fma_f32 v[154:155], v[180:181], v[154:155], v[130:131]
	v_pk_fma_f32 v[152:153], v[182:183], v[152:153], v[128:129]
	global_load_dwordx4 v[156:159], v[158:159], off offset:3072
	s_waitcnt vmcnt(1)
	v_pk_add_f32 v[182:183], v[250:251], 0 op_sel_hi:[1,0]
	v_pk_add_f32 v[180:181], v[248:249], 0 op_sel_hi:[1,0]
	global_load_dwordx4 v[248:251], v[160:161], off offset:3072
	s_waitcnt vmcnt(1)
	v_pk_add_f32 v[182:183], v[182:183], v[158:159]
	v_pk_add_f32 v[180:181], v[180:181], v[156:157]
	global_load_dwordx4 v[156:159], v[162:163], off offset:3072
	s_waitcnt vmcnt(1)
	v_pk_add_f32 v[160:161], v[182:183], v[250:251]
	v_pk_add_f32 v[180:181], v[180:181], v[248:249]
	global_load_dwordx4 v[248:251], v[236:237], off offset:3072
	s_waitcnt vmcnt(1)
	v_pk_add_f32 v[160:161], v[160:161], v[158:159]
	v_pk_add_f32 v[162:163], v[180:181], v[156:157]
	global_load_dwordx4 v[156:159], v[238:239], off offset:3072
	s_waitcnt vmcnt(1)
	v_pk_add_f32 v[160:161], v[160:161], v[250:251]
	v_pk_add_f32 v[162:163], v[162:163], v[248:249]
	global_load_dwordx4 v[248:251], v[240:241], off offset:3072
	s_waitcnt vmcnt(1)
	v_pk_add_f32 v[160:161], v[160:161], v[158:159]
	v_pk_add_f32 v[162:163], v[162:163], v[156:157]
	global_load_dwordx4 v[156:159], v[242:243], off offset:3072
	s_waitcnt vmcnt(1)
	v_pk_add_f32 v[160:161], v[160:161], v[250:251]
	v_pk_add_f32 v[162:163], v[162:163], v[248:249]
	global_load_dwordx4 v[248:251], v[230:231], off offset:-1024
	s_waitcnt vmcnt(1)
	v_pk_add_f32 v[160:161], v[160:161], v[158:159]
	v_pk_add_f32 v[236:237], v[162:163], v[156:157]
	s_waitcnt vmcnt(0)
	v_pk_fma_f32 v[162:163], v[160:161], v[250:251], v[126:127]
	v_pk_fma_f32 v[160:161], v[236:237], v[248:249], v[124:125]
	v_add_co_u32_e32 v156, vcc, s1, v232
	v_ashrrev_i32_e32 v237, 31, v186
	s_nop 0
	v_addc_co_u32_e32 v157, vcc, -1, v233, vcc
	global_store_dwordx4 v[156:157], v[92:95], off offset:-3072 sc1
	global_store_dwordx4 v[156:157], v[132:135], off offset:-2048 sc1
	global_store_dwordx4 v[156:157], v[136:139], off offset:-1024 sc1
	global_store_dwordx4 v[232:233], v[140:143], off offset:-4096 sc1
	global_store_dwordx4 v[232:233], v[144:147], off offset:-3072 sc1
	global_store_dwordx4 v[232:233], v[148:151], off offset:-2048 sc1
	global_store_dwordx4 v[232:233], v[152:155], off offset:-1024 sc1
	global_store_dwordx4 v[232:233], v[160:163], off sc1
	v_mov_b64_e32 v[156:157], v[160:161]
	v_mov_b32_e32 v236, v186
	v_mov_b64_e32 v[158:159], v[162:163]
	s_cbranch_execnz .LBB0_88
	s_branch .LBB0_95

.LBB0_106:
	v_ashrrev_i32_e32 v32, 10, v177
	s_mul_i32 s1, s22, 5
	v_add_u32_e32 v34, s1, v32
	v_mov_b64_e32 v[32:33], s[42:43]
	v_mad_i64_i32 v[112:113], s[8:9], v34, s3, v[32:33]
	v_lshl_add_u64 v[80:81], v[112:113], 0, v[174:175]
	v_add_co_u32_e32 v82, vcc, s18, v80
	v_ashrrev_i32_e32 v123, 31, v122
	s_nop 0
	v_addc_co_u32_e32 v83, vcc, 0, v81, vcc
	global_load_dwordx4 v[36:39], v[82:83], off
	v_add_u32_e32 v140, 1, v122
	v_lshlrev_b64 v[32:33], 13, v[122:123]
	v_ashrrev_i32_e32 v141, 31, v140
	v_lshl_add_u64 v[108:109], s[40:41], 0, v[32:33]
	v_lshlrev_b64 v[32:33], 13, v[140:141]
	v_lshl_add_u64 v[110:111], s[40:41], 0, v[32:33]
	v_lshl_add_u64 v[60:61], v[108:109], 0, v[174:175]
	v_lshl_add_u64 v[62:63], v[110:111], 0, v[174:175]
	global_load_dwordx4 v[64:67], v[60:61], off
	global_load_dwordx4 v[32:35], v[62:63], off
	v_mov_b32_e32 v165, v175
	v_lshl_add_u64 v[88:89], v[112:113], 0, v[164:165]
	v_add_co_u32_e32 v84, vcc, s18, v88
	v_mov_b32_e32 v167, v175
	s_nop 0
	v_addc_co_u32_e32 v85, vcc, 0, v89, vcc
	v_lshl_add_u64 v[96:97], v[112:113], 0, v[166:167]
	v_add_co_u32_e32 v92, vcc, s18, v96
	v_mov_b32_e32 v169, v175
	s_nop 0
	v_addc_co_u32_e32 v93, vcc, 0, v97, vcc
	v_lshl_add_u64 v[114:115], v[112:113], 0, v[168:169]
	v_add_co_u32_e32 v100, vcc, s18, v114
	v_mov_b32_e32 v171, v175
	s_nop 0
	v_addc_co_u32_e32 v101, vcc, 0, v115, vcc
	v_lshl_add_u64 v[184:185], v[112:113], 0, v[170:171]
	v_add_co_u32_e32 v112, vcc, s18, v184
	v_add_u32_e32 v177, s6, v177
	s_nop 0
	v_addc_co_u32_e32 v113, vcc, 0, v185, vcc
	s_waitcnt vmcnt(2)
	v_pk_add_f32 v[38:39], v[38:39], 1.0 op_sel_hi:[1,0]
	v_pk_add_f32 v[36:37], v[36:37], 1.0 op_sel_hi:[1,0]
	v_pk_mul_f32 v[124:125], v[2:3], v[38:39]
	v_pk_mul_f32 v[126:127], v[0:1], v[36:37]
	global_load_dwordx4 v[48:51], v[80:81], off
	global_load_dwordx4 v[68:71], v[60:61], off offset:1024
	global_load_dwordx4 v[36:39], v[62:63], off offset:1024
	global_load_dwordx4 v[40:43], v[82:83], off offset:1024
	s_waitcnt vmcnt(5)
	v_mov_b32_e32 v188, v65
	v_mov_b32_e32 v186, v64
	v_mov_b32_e32 v190, v67
	s_waitcnt vmcnt(2)
	v_mov_b32_e32 v189, v69
	v_mov_b32_e32 v187, v68
	s_waitcnt vmcnt(0)
	v_pk_add_f32 v[42:43], v[42:43], 1.0 op_sel_hi:[1,0]
	v_pk_add_f32 v[40:41], v[40:41], 1.0 op_sel_hi:[1,0]
	v_pk_mul_f32 v[128:129], v[6:7], v[42:43]
	v_pk_mul_f32 v[130:131], v[4:5], v[40:41]
	global_load_dwordx4 v[52:55], v[80:81], off offset:1024
	global_load_dwordx4 v[72:75], v[60:61], off offset:2048
	global_load_dwordx4 v[40:43], v[62:63], off offset:2048
	global_load_dwordx4 v[44:47], v[82:83], off offset:2048
	v_pk_mul_f32 v[188:189], v[188:189], v[188:189]
	v_mov_b32_e32 v191, v71
	v_pk_fma_f32 v[186:187], v[186:187], v[186:187], v[188:189]
	v_mov_b32_e32 v188, v66
	v_mov_b32_e32 v189, v70
	v_pk_mul_f32 v[190:191], v[190:191], v[190:191]
	s_waitcnt vmcnt(0)
	v_pk_add_f32 v[46:47], v[46:47], 1.0 op_sel_hi:[1,0]
	v_pk_add_f32 v[44:45], v[44:45], 1.0 op_sel_hi:[1,0]
	v_pk_mul_f32 v[132:133], v[10:11], v[46:47]
	v_pk_mul_f32 v[134:135], v[8:9], v[44:45]
	global_load_dwordx4 v[56:59], v[80:81], off offset:2048
	global_load_dwordx4 v[76:79], v[60:61], off offset:3072
	global_load_dwordx4 v[44:47], v[62:63], off offset:3072
	s_nop 0
	global_load_dwordx4 v[60:63], v[82:83], off offset:3072
	v_pk_fma_f32 v[188:189], v[188:189], v[188:189], v[190:191]
	v_pk_mul_f32 v[190:191], v[72:73], v[72:73]
	v_pk_add_f32 v[186:187], v[186:187], v[188:189]
	v_pk_mul_f32 v[188:189], v[74:75], v[74:75]
	v_pk_add_f32 v[186:187], v[186:187], v[186:187] op_sel:[0,1] op_sel_hi:[1,0]
	v_pk_mov_b32 v[192:193], v[190:191], v[188:189] op_sel:[1,0]
	v_mov_b32_e32 v191, v189
	v_pk_add_f32 v[188:189], v[192:193], v[190:191]
	global_load_dwordx4 v[84:87], v[84:85], off
	v_pk_add_f32 v[188:189], v[188:189], v[188:189] op_sel:[0,1] op_sel_hi:[1,0]
	global_load_dwordx4 v[92:95], v[92:93], off
	s_waitcnt vmcnt(4)
	v_mul_f32_e32 v190, v79, v79
	v_pk_fma_f32 v[190:191], v[78:79], v[78:79], v[190:191] op_sel_hi:[1,1,0]
	s_waitcnt vmcnt(2)
	v_pk_add_f32 v[62:63], v[62:63], 1.0 op_sel_hi:[1,0]
	v_pk_add_f32 v[60:61], v[60:61], 1.0 op_sel_hi:[1,0]
	v_pk_mul_f32 v[136:137], v[14:15], v[62:63]
	v_pk_mul_f32 v[138:139], v[12:13], v[60:61]
	global_load_dwordx4 v[60:63], v[80:81], off offset:3072
	v_lshl_add_u64 v[80:81], v[108:109], 0, v[164:165]
	global_load_dwordx4 v[104:107], v[80:81], off
	v_lshl_add_u64 v[80:81], v[110:111], 0, v[164:165]
	global_load_dwordx4 v[80:83], v[80:81], off
	s_waitcnt vmcnt(4)
	v_pk_add_f32 v[86:87], v[86:87], 1.0 op_sel_hi:[1,0]
	v_pk_add_f32 v[84:85], v[84:85], 1.0 op_sel_hi:[1,0]
	v_pk_mul_f32 v[142:143], v[18:19], v[86:87]
	v_pk_mul_f32 v[144:145], v[16:17], v[84:85]
	global_load_dwordx4 v[84:87], v[88:89], off
	v_lshl_add_u64 v[88:89], v[108:109], 0, v[166:167]
	global_load_dwordx4 v[116:119], v[88:89], off
	v_lshl_add_u64 v[88:89], v[110:111], 0, v[166:167]
	global_load_dwordx4 v[88:91], v[88:89], off
	s_waitcnt vmcnt(6)
	v_pk_add_f32 v[94:95], v[94:95], 1.0 op_sel_hi:[1,0]
	v_pk_add_f32 v[92:93], v[92:93], 1.0 op_sel_hi:[1,0]
	v_pk_mul_f32 v[146:147], v[22:23], v[94:95]
	v_pk_mul_f32 v[148:149], v[20:21], v[92:93]
	global_load_dwordx4 v[92:95], v[96:97], off
	s_waitcnt vmcnt(5)
	v_mul_f32_e32 v159, v105, v105
	global_load_dwordx4 v[100:103], v[100:101], off
	v_lshl_add_u64 v[96:97], v[108:109], 0, v[168:169]
	v_lshl_add_u64 v[108:109], v[108:109], 0, v[170:171]
	v_mov_b32_e32 v189, v159
	v_mul_f32_e32 v165, v106, v106
	v_mul_f32_e32 v167, v107, v107
	v_mov_b32_e32 v191, v167
	global_load_dwordx4 v[160:163], v[96:97], off
	global_load_dwordx4 v[180:183], v[108:109], off
	v_lshl_add_u64 v[96:97], v[110:111], 0, v[168:169]
	v_lshl_add_u64 v[108:109], v[110:111], 0, v[170:171]
	global_load_dwordx4 v[96:99], v[96:97], off
	s_waitcnt vmcnt(3)
	v_pk_add_f32 v[102:103], v[102:103], 1.0 op_sel_hi:[1,0]
	v_pk_add_f32 v[100:101], v[100:101], 1.0 op_sel_hi:[1,0]
	global_load_dwordx4 v[108:111], v[108:109], off
	v_pk_mul_f32 v[150:151], v[26:27], v[102:103]
	v_pk_mul_f32 v[152:153], v[24:25], v[100:101]
	global_load_dwordx4 v[100:103], v[114:115], off
	s_waitcnt vmcnt(3)
	v_mul_f32_e32 v159, v181, v181
	global_load_dwordx4 v[112:115], v[112:113], off
	v_mul_f32_e32 v167, v183, v183
	s_waitcnt vmcnt(0)
	v_pk_add_f32 v[114:115], v[114:115], 1.0 op_sel_hi:[1,0]
	v_pk_add_f32 v[112:113], v[112:113], 1.0 op_sel_hi:[1,0]
	v_pk_mul_f32 v[154:155], v[30:31], v[114:115]
	v_pk_mul_f32 v[156:157], v[28:29], v[112:113]
	global_load_dwordx4 v[112:115], v[184:185], off
	v_lshlrev_b64 v[184:185], 12, v[122:123]
	v_mul_f32_e32 v123, v104, v104
	v_add_u32_e32 v122, s4, v122
	v_mov_b32_e32 v187, v123
	v_mul_f32_e32 v123, v180, v180
	v_pk_add_f32 v[186:187], v[186:187], v[188:189]
	v_mul_f32_e32 v188, v77, v77
	v_pk_fma_f32 v[188:189], v[76:77], v[76:77], v[188:189] op_sel_hi:[1,1,0]
	s_nop 0
	v_mov_b32_e32 v189, v165
	v_mul_f32_e32 v165, v182, v182
	v_pk_add_f32 v[188:189], v[188:189], v[190:191]
	v_pk_mul_f32 v[190:191], v[116:117], v[116:117]
	v_pk_add_f32 v[186:187], v[186:187], v[188:189]
	v_pk_mul_f32 v[188:189], v[118:119], v[118:119]
	v_pk_add_f32 v[186:187], v[186:187], v[186:187] op_sel:[0,1] op_sel_hi:[1,0]
	v_pk_mov_b32 v[192:193], v[190:191], v[188:189] op_sel:[1,0]
	v_mov_b32_e32 v191, v189
	v_pk_add_f32 v[188:189], v[192:193], v[190:191]
	v_mov_b32_e32 v187, v123
	v_mul_f32_e32 v190, v163, v163
	v_pk_add_f32 v[188:189], v[188:189], v[188:189] op_sel:[0,1] op_sel_hi:[1,0]
	v_pk_fma_f32 v[190:191], v[162:163], v[162:163], v[190:191] op_sel_hi:[1,1,0]
	v_mov_b32_e32 v189, v159
	v_mov_b32_e32 v191, v167
	v_pk_add_f32 v[186:187], v[186:187], v[188:189]
	v_mul_f32_e32 v188, v161, v161
	v_pk_fma_f32 v[188:189], v[160:161], v[160:161], v[188:189] op_sel_hi:[1,1,0]
	s_nop 0
	v_mov_b32_e32 v189, v165
	v_pk_add_f32 v[188:189], v[188:189], v[190:191]
	s_nop 0
	v_pk_add_f32 v[186:187], v[186:187], v[188:189]
	s_nop 0
	v_add_f32_e32 v123, v186, v187
	s_nop 1
	v_add_f32_dpp v123, v123, v123 row_ror:8 row_mask:0xf bank_mask:0xf bound_ctrl:1
	s_nop 1
	v_add_f32_dpp v123, v123, v123 row_ror:4 row_mask:0xf bank_mask:0xf bound_ctrl:1
	s_nop 1
	v_add_f32_dpp v123, v123, v123 row_ror:2 row_mask:0xf bank_mask:0xf bound_ctrl:1
	s_nop 1
	v_add_f32_dpp v123, v123, v123 row_ror:1 row_mask:0xf bank_mask:0xf bound_ctrl:1
	s_nop 0
	v_readlane_b32 s1, v123, 16
	v_readlane_b32 s2, v123, 48
	v_readlane_b32 s8, v123, 0
	v_readlane_b32 s9, v123, 32
	v_mov_b32_e32 v186, s1
	v_mov_b32_e32 v187, s2
	v_pk_add_f32 v[186:187], s[8:9], v[186:187]
	s_nop 0
	v_add_f32_e32 v123, v186, v187
	v_fmamk_f32 v123, v123, 0x3a000000, v173
	v_cmp_gt_f32_e32 vcc, s19, v123
	v_mul_f32_e32 v159, 0x4f800000, v123
	s_nop 0
	v_cndmask_b32_e32 v123, v123, v159, vcc
	v_sqrt_f32_e32 v159, v123
	s_nop 0
	v_add_u32_e32 v165, -1, v159
	v_fma_f32 v167, -v165, v159, v123
	v_cmp_ge_f32_e64 s[36:37], 0, v167
	v_add_u32_e32 v167, 1, v159
	s_nop 0
	v_cndmask_b32_e64 v165, v159, v165, s[36:37]
	v_fma_f32 v159, -v167, v159, v123
	v_cmp_lt_f32_e64 s[36:37], 0, v159
	s_nop 1
	v_cndmask_b32_e64 v159, v165, v167, s[36:37]
	v_mul_f32_e32 v165, 0x37800000, v159
	v_cndmask_b32_e32 v159, v159, v165, vcc
	v_cmp_class_f32_e32 vcc, v123, v244
	s_nop 1
	v_cndmask_b32_e32 v123, v159, v123, vcc
	v_div_scale_f32 v159, s[8:9], v123, v123, 1.0
	v_rcp_f32_e32 v165, v159
	s_nop 0
	v_fma_f32 v167, -v159, v165, 1.0
	v_fmac_f32_e32 v165, v167, v165
	v_div_scale_f32 v167, vcc, 1.0, v123, 1.0
	v_mul_f32_e32 v169, v167, v165
	v_fma_f32 v171, -v159, v169, v167
	v_fmac_f32_e32 v169, v171, v165
	v_fma_f32 v159, -v159, v169, v167
	v_div_fmas_f32 v159, v159, v165, v169
	v_div_fixup_f32 v186, v159, v123, 1.0
	v_pk_mul_f32 v[64:65], v[64:65], v[186:187] op_sel_hi:[1,0]
	v_pk_mul_f32 v[66:67], v[66:67], v[186:187] op_sel_hi:[1,0]
	v_pk_fma_f32 v[64:65], v[126:127], v[64:65], v[48:49]
	v_pk_fma_f32 v[66:67], v[124:125], v[66:67], v[50:51]
	v_cvt_pk_bf16_f32 v64, v64, v65
	s_nop 0
	v_cvt_pk_bf16_f32 v65, v66, v67
	v_lshl_add_u64 v[66:67], v[120:121], 0, v[184:185]
	global_store_dwordx2 v[66:67], v[64:65], off sc1
	v_pk_mul_f32 v[64:65], v[68:69], v[186:187] op_sel_hi:[1,0]
	v_pk_mul_f32 v[68:69], v[70:71], v[186:187] op_sel_hi:[1,0]
	v_pk_fma_f32 v[64:65], v[130:131], v[64:65], v[52:53]
	v_pk_fma_f32 v[68:69], v[128:129], v[68:69], v[54:55]
	v_cvt_pk_bf16_f32 v64, v64, v65
	v_mov_b32_e32 v70, v35
	v_cvt_pk_bf16_f32 v65, v68, v69
	global_store_dwordx2 v[66:67], v[64:65], off offset:512 sc1
	v_pk_mul_f32 v[64:65], v[72:73], v[186:187] op_sel_hi:[1,0]
	v_pk_mul_f32 v[68:69], v[74:75], v[186:187] op_sel_hi:[1,0]
	v_pk_fma_f32 v[64:65], v[134:135], v[64:65], v[56:57]
	v_pk_fma_f32 v[68:69], v[132:133], v[68:69], v[58:59]
	v_cvt_pk_bf16_f32 v64, v64, v65
	v_mov_b32_e32 v71, v39
	v_cvt_pk_bf16_f32 v65, v68, v69
	global_store_dwordx2 v[66:67], v[64:65], off offset:1024 sc1
	v_pk_mul_f32 v[64:65], v[76:77], v[186:187] op_sel_hi:[1,0]
	v_pk_mul_f32 v[68:69], v[78:79], v[186:187] op_sel_hi:[1,0]
	v_pk_fma_f32 v[64:65], v[138:139], v[64:65], v[60:61]
	v_pk_fma_f32 v[68:69], v[136:137], v[68:69], v[62:63]
	v_cvt_pk_bf16_f32 v64, v64, v65
	v_pk_mul_f32 v[70:71], v[70:71], v[70:71]
	v_cvt_pk_bf16_f32 v65, v68, v69
	global_store_dwordx2 v[66:67], v[64:65], off offset:1536 sc1
	v_pk_mul_f32 v[64:65], v[104:105], v[186:187] op_sel_hi:[1,0]
	v_pk_mul_f32 v[68:69], v[106:107], v[186:187] op_sel_hi:[1,0]
	v_pk_fma_f32 v[64:65], v[144:145], v[64:65], v[84:85]
	v_pk_fma_f32 v[68:69], v[142:143], v[68:69], v[86:87]
	v_cvt_pk_bf16_f32 v64, v64, v65
	s_nop 0
	v_cvt_pk_bf16_f32 v65, v68, v69
	global_store_dwordx2 v[66:67], v[64:65], off offset:2048 sc1
	v_pk_mul_f32 v[64:65], v[116:117], v[186:187] op_sel_hi:[1,0]
	v_pk_mul_f32 v[68:69], v[118:119], v[186:187] op_sel_hi:[1,0]
	v_pk_fma_f32 v[64:65], v[148:149], v[64:65], v[92:93]
	v_pk_fma_f32 v[68:69], v[146:147], v[68:69], v[94:95]
	v_cvt_pk_bf16_f32 v64, v64, v65
	s_nop 0
	v_cvt_pk_bf16_f32 v65, v68, v69
	global_store_dwordx2 v[66:67], v[64:65], off offset:2560 sc1
	v_pk_mul_f32 v[64:65], v[160:161], v[186:187] op_sel_hi:[1,0]
	v_pk_mul_f32 v[68:69], v[162:163], v[186:187] op_sel_hi:[1,0]
	v_pk_fma_f32 v[64:65], v[152:153], v[64:65], v[100:101]
	v_pk_fma_f32 v[68:69], v[150:151], v[68:69], v[102:103]
	v_cvt_pk_bf16_f32 v64, v64, v65
	s_nop 0
	v_cvt_pk_bf16_f32 v65, v68, v69
	global_store_dwordx2 v[66:67], v[64:65], off offset:3072 sc1
	v_pk_mul_f32 v[64:65], v[180:181], v[186:187] op_sel_hi:[1,0]
	v_pk_mul_f32 v[68:69], v[182:183], v[186:187] op_sel_hi:[1,0]
	s_waitcnt vmcnt(7)
	v_pk_fma_f32 v[64:65], v[156:157], v[64:65], v[112:113]
	v_pk_fma_f32 v[68:69], v[154:155], v[68:69], v[114:115]
	v_cvt_pk_bf16_f32 v64, v64, v65
	s_nop 0
	v_cvt_pk_bf16_f32 v65, v68, v69
	v_mov_b32_e32 v68, v33
	v_mov_b32_e32 v69, v37
	global_store_dwordx2 v[66:67], v[64:65], off offset:3584 sc1
	v_mov_b32_e32 v66, v32
	v_mov_b32_e32 v67, v36
	v_pk_mul_f32 v[68:69], v[68:69], v[68:69]
	v_lshlrev_b64 v[64:65], 12, v[140:141]
	v_pk_fma_f32 v[66:67], v[66:67], v[66:67], v[68:69]
	v_mov_b32_e32 v68, v34
	v_mov_b32_e32 v69, v38
	v_pk_fma_f32 v[68:69], v[68:69], v[68:69], v[70:71]
	v_pk_mul_f32 v[70:71], v[40:41], v[40:41]
	v_pk_add_f32 v[66:67], v[66:67], v[68:69]
	v_pk_mul_f32 v[68:69], v[42:43], v[42:43]
	v_pk_add_f32 v[66:67], v[66:67], v[66:67] op_sel:[0,1] op_sel_hi:[1,0]
	v_pk_mov_b32 v[72:73], v[70:71], v[68:69] op_sel:[1,0]
	v_mov_b32_e32 v71, v69
	v_pk_add_f32 v[68:69], v[72:73], v[70:71]
	v_mul_f32_e32 v70, v80, v80
	v_mul_f32_e32 v71, v81, v81
	v_pk_add_f32 v[68:69], v[68:69], v[68:69] op_sel:[0,1] op_sel_hi:[1,0]
	v_mov_b32_e32 v67, v70
	v_mov_b32_e32 v69, v71
	v_pk_add_f32 v[66:67], v[66:67], v[68:69]
	v_mul_f32_e32 v68, v45, v45
	v_mul_f32_e32 v70, v47, v47
	v_mul_f32_e32 v72, v82, v82
	v_mul_f32_e32 v73, v83, v83
	v_pk_fma_f32 v[68:69], v[44:45], v[44:45], v[68:69] op_sel_hi:[1,1,0]
	v_pk_fma_f32 v[70:71], v[46:47], v[46:47], v[70:71] op_sel_hi:[1,1,0]
	v_mov_b32_e32 v69, v72
	v_mov_b32_e32 v71, v73
	v_pk_add_f32 v[68:69], v[68:69], v[70:71]
	v_pk_mul_f32 v[70:71], v[88:89], v[88:89]
	v_pk_add_f32 v[66:67], v[66:67], v[68:69]
	v_pk_mul_f32 v[68:69], v[90:91], v[90:91]
	v_pk_add_f32 v[66:67], v[66:67], v[66:67] op_sel:[0,1] op_sel_hi:[1,0]
	v_pk_mov_b32 v[72:73], v[70:71], v[68:69] op_sel:[1,0]
	v_mov_b32_e32 v71, v69
	v_pk_add_f32 v[68:69], v[72:73], v[70:71]
	v_mul_f32_e32 v70, v108, v108
	v_mul_f32_e32 v71, v109, v109
	v_pk_add_f32 v[68:69], v[68:69], v[68:69] op_sel:[0,1] op_sel_hi:[1,0]
	v_mov_b32_e32 v67, v70
	v_mov_b32_e32 v69, v71
	v_pk_add_f32 v[66:67], v[66:67], v[68:69]
	v_mul_f32_e32 v68, v97, v97
	v_mul_f32_e32 v70, v99, v99
	v_mul_f32_e32 v72, v110, v110
	v_mul_f32_e32 v73, v111, v111
	v_pk_fma_f32 v[68:69], v[96:97], v[96:97], v[68:69] op_sel_hi:[1,1,0]
	v_pk_fma_f32 v[70:71], v[98:99], v[98:99], v[70:71] op_sel_hi:[1,1,0]
	v_mov_b32_e32 v69, v72
	v_mov_b32_e32 v71, v73
	v_pk_add_f32 v[68:69], v[68:69], v[70:71]
	s_nop 0
	v_pk_add_f32 v[66:67], v[66:67], v[68:69]
	s_nop 0
	v_add_f32_e32 v66, v66, v67
	s_nop 1
	v_add_f32_dpp v66, v66, v66 row_ror:8 row_mask:0xf bank_mask:0xf bound_ctrl:1
	s_nop 1
	v_add_f32_dpp v66, v66, v66 row_ror:4 row_mask:0xf bank_mask:0xf bound_ctrl:1
	s_nop 1
	v_add_f32_dpp v66, v66, v66 row_ror:2 row_mask:0xf bank_mask:0xf bound_ctrl:1
	s_nop 1
	v_add_f32_dpp v66, v66, v66 row_ror:1 row_mask:0xf bank_mask:0xf bound_ctrl:1
	s_nop 0
	v_readlane_b32 s1, v66, 16
	v_readlane_b32 s2, v66, 48
	v_readlane_b32 s8, v66, 0
	v_readlane_b32 s9, v66, 32
	v_mov_b32_e32 v66, s1
	v_mov_b32_e32 v67, s2
	v_pk_add_f32 v[66:67], s[8:9], v[66:67]
	s_nop 0
	v_add_f32_e32 v66, v66, v67
	v_fmamk_f32 v66, v66, 0x3a000000, v173
	v_cmp_gt_f32_e32 vcc, s19, v66
	v_mul_f32_e32 v67, 0x4f800000, v66
	s_nop 0
	v_cndmask_b32_e32 v66, v66, v67, vcc
	v_sqrt_f32_e32 v67, v66
	s_nop 0
	v_add_u32_e32 v68, -1, v67
	v_fma_f32 v69, -v68, v67, v66
	v_cmp_ge_f32_e64 s[36:37], 0, v69
	v_add_u32_e32 v69, 1, v67
	s_nop 0
	v_cndmask_b32_e64 v68, v67, v68, s[36:37]
	v_fma_f32 v67, -v69, v67, v66
	v_cmp_lt_f32_e64 s[36:37], 0, v67
	s_nop 1
	v_cndmask_b32_e64 v67, v68, v69, s[36:37]
	v_mul_f32_e32 v68, 0x37800000, v67
	v_cndmask_b32_e32 v67, v67, v68, vcc
	v_cmp_class_f32_e32 vcc, v66, v244
	s_nop 1
	v_cndmask_b32_e32 v66, v67, v66, vcc
	v_div_scale_f32 v67, s[8:9], v66, v66, 1.0
	v_rcp_f32_e32 v68, v67
	s_nop 0
	v_fma_f32 v69, -v67, v68, 1.0
	v_fmac_f32_e32 v68, v69, v68
	v_div_scale_f32 v69, vcc, 1.0, v66, 1.0
	v_mul_f32_e32 v70, v69, v68
	v_fma_f32 v71, -v67, v70, v69
	v_fmac_f32_e32 v70, v71, v68
	v_fma_f32 v67, -v67, v70, v69
	v_div_fmas_f32 v67, v67, v68, v70
	v_div_fixup_f32 v66, v67, v66, 1.0
	v_pk_mul_f32 v[32:33], v[32:33], v[66:67] op_sel_hi:[1,0]
	v_pk_mul_f32 v[34:35], v[34:35], v[66:67] op_sel_hi:[1,0]
	v_pk_fma_f32 v[32:33], v[126:127], v[32:33], v[48:49]
	v_pk_fma_f32 v[34:35], v[124:125], v[34:35], v[50:51]
	v_cvt_pk_bf16_f32 v32, v32, v33
	v_cmp_ge_i32_e32 vcc, v177, v158
	v_cvt_pk_bf16_f32 v33, v34, v35
	v_lshl_add_u64 v[34:35], v[120:121], 0, v[64:65]
	global_store_dwordx2 v[34:35], v[32:33], off sc1
	v_pk_mul_f32 v[32:33], v[36:37], v[66:67] op_sel_hi:[1,0]
	v_pk_mul_f32 v[36:37], v[38:39], v[66:67] op_sel_hi:[1,0]
	v_pk_fma_f32 v[32:33], v[130:131], v[32:33], v[52:53]
	v_pk_fma_f32 v[36:37], v[128:129], v[36:37], v[54:55]
	v_cvt_pk_bf16_f32 v32, v32, v33
	s_or_b64 s[38:39], vcc, s[38:39]
	v_cvt_pk_bf16_f32 v33, v36, v37
	global_store_dwordx2 v[34:35], v[32:33], off offset:512 sc1
	v_pk_mul_f32 v[32:33], v[40:41], v[66:67] op_sel_hi:[1,0]
	v_pk_mul_f32 v[36:37], v[42:43], v[66:67] op_sel_hi:[1,0]
	v_pk_fma_f32 v[32:33], v[134:135], v[32:33], v[56:57]
	v_pk_fma_f32 v[36:37], v[132:133], v[36:37], v[58:59]
	v_cvt_pk_bf16_f32 v32, v32, v33
	s_nop 0
	v_cvt_pk_bf16_f32 v33, v36, v37
	global_store_dwordx2 v[34:35], v[32:33], off offset:1024 sc1
	v_pk_mul_f32 v[32:33], v[44:45], v[66:67] op_sel_hi:[1,0]
	v_pk_mul_f32 v[36:37], v[46:47], v[66:67] op_sel_hi:[1,0]
	v_pk_fma_f32 v[32:33], v[138:139], v[32:33], v[60:61]
	v_pk_fma_f32 v[36:37], v[136:137], v[36:37], v[62:63]
	v_cvt_pk_bf16_f32 v32, v32, v33
	s_nop 0
	v_cvt_pk_bf16_f32 v33, v36, v37
	global_store_dwordx2 v[34:35], v[32:33], off offset:1536 sc1
	v_pk_mul_f32 v[32:33], v[80:81], v[66:67] op_sel_hi:[1,0]
	v_pk_mul_f32 v[36:37], v[82:83], v[66:67] op_sel_hi:[1,0]
	v_pk_fma_f32 v[32:33], v[144:145], v[32:33], v[84:85]
	v_pk_fma_f32 v[36:37], v[142:143], v[36:37], v[86:87]
	v_cvt_pk_bf16_f32 v32, v32, v33
	s_nop 0
	v_cvt_pk_bf16_f32 v33, v36, v37
	global_store_dwordx2 v[34:35], v[32:33], off offset:2048 sc1
	v_pk_mul_f32 v[32:33], v[88:89], v[66:67] op_sel_hi:[1,0]
	v_pk_mul_f32 v[36:37], v[90:91], v[66:67] op_sel_hi:[1,0]
	v_pk_fma_f32 v[32:33], v[148:149], v[32:33], v[92:93]
	v_pk_fma_f32 v[36:37], v[146:147], v[36:37], v[94:95]
	v_cvt_pk_bf16_f32 v32, v32, v33
	s_nop 0
	v_cvt_pk_bf16_f32 v33, v36, v37
	global_store_dwordx2 v[34:35], v[32:33], off offset:2560 sc1
	v_pk_mul_f32 v[32:33], v[96:97], v[66:67] op_sel_hi:[1,0]
	v_pk_mul_f32 v[36:37], v[98:99], v[66:67] op_sel_hi:[1,0]
	v_pk_fma_f32 v[32:33], v[152:153], v[32:33], v[100:101]
	v_pk_fma_f32 v[36:37], v[150:151], v[36:37], v[102:103]
	v_cvt_pk_bf16_f32 v32, v32, v33
	s_nop 0
	v_cvt_pk_bf16_f32 v33, v36, v37
	global_store_dwordx2 v[34:35], v[32:33], off offset:3072 sc1
	v_pk_mul_f32 v[32:33], v[108:109], v[66:67] op_sel_hi:[1,0]
	v_pk_mul_f32 v[36:37], v[110:111], v[66:67] op_sel_hi:[1,0]
	v_pk_fma_f32 v[32:33], v[156:157], v[32:33], v[112:113]
	v_pk_fma_f32 v[36:37], v[154:155], v[36:37], v[114:115]
	v_cvt_pk_bf16_f32 v32, v32, v33
	s_nop 0
	v_cvt_pk_bf16_f32 v33, v36, v37
	global_store_dwordx2 v[34:35], v[32:33], off offset:3584 sc1
	s_andn2_b64 exec, exec, s[38:39]
	s_cbranch_execnz .LBB0_106
